# Epi3 first row statistics: the 16 serial cross-lane round trips batched into 2 (same arithmetic)
# speedup vs baseline: 1.0097x; 1.0097x over previous
.LBB0_631:
	v_cmp_lt_i32_e32 vcc, v221, v223
	v_mov_b32_e32 v3, v211
	v_cmp_eq_u32_e64 s[8:9], 0, v3
	v_mov_b32_e32 v2, v210
	v_cndmask_b32_e32 v0, v219, v221, vcc
	v_lshlrev_b32_e32 v215, 2, v0
	v_cmp_lt_i32_e32 vcc, v224, v223
	v_mov_b32_e32 v0, v2
	v_add_u32_e32 v188, s61, v0
	v_cndmask_b32_e32 v133, v219, v224, vcc
	v_lshlrev_b32_e32 v245, 2, v133
	v_mul_f32_e32 v134, v129, v129
	v_fmac_f32_e32 v134, v128, v128
	v_fmac_f32_e32 v134, v130, v130
	v_fmac_f32_e32 v134, v131, v131
	v_mul_f32_e32 v132, v125, v125
	v_fmac_f32_e32 v132, v124, v124
	v_fmac_f32_e32 v132, v126, v126
	v_fmac_f32_e32 v132, v127, v127
	v_add_f32_e32 v134, v132, v134
	v_mul_f32_e32 v132, v97, v97
	v_fmac_f32_e32 v132, v96, v96
	v_fmac_f32_e32 v132, v98, v98
	v_fmac_f32_e32 v132, v99, v99
	v_add_f32_e32 v134, v132, v134
	v_mul_f32_e32 v132, v93, v93
	v_fmac_f32_e32 v132, v92, v92
	v_fmac_f32_e32 v132, v94, v94
	v_fmac_f32_e32 v132, v95, v95
	v_add_f32_e32 v134, v132, v134
	v_mul_f32_e32 v135, v121, v121
	v_fmac_f32_e32 v135, v120, v120
	v_fmac_f32_e32 v135, v122, v122
	v_fmac_f32_e32 v135, v123, v123
	v_mul_f32_e32 v132, v117, v117
	v_fmac_f32_e32 v132, v116, v116
	v_fmac_f32_e32 v132, v118, v118
	v_fmac_f32_e32 v132, v119, v119
	v_add_f32_e32 v135, v132, v135
	v_mul_f32_e32 v132, v89, v89
	v_fmac_f32_e32 v132, v88, v88
	v_fmac_f32_e32 v132, v90, v90
	v_fmac_f32_e32 v132, v91, v91
	v_add_f32_e32 v135, v132, v135
	v_mul_f32_e32 v132, v85, v85
	v_fmac_f32_e32 v132, v84, v84
	v_fmac_f32_e32 v132, v86, v86
	v_fmac_f32_e32 v132, v87, v87
	v_add_f32_e32 v135, v132, v135
	v_mul_f32_e32 v136, v113, v113
	v_fmac_f32_e32 v136, v112, v112
	v_fmac_f32_e32 v136, v114, v114
	v_fmac_f32_e32 v136, v115, v115
	v_mul_f32_e32 v132, v109, v109
	v_fmac_f32_e32 v132, v108, v108
	v_fmac_f32_e32 v132, v110, v110
	v_fmac_f32_e32 v132, v111, v111
	v_add_f32_e32 v136, v132, v136
	v_mul_f32_e32 v132, v81, v81
	v_fmac_f32_e32 v132, v80, v80
	v_fmac_f32_e32 v132, v82, v82
	v_fmac_f32_e32 v132, v83, v83
	v_add_f32_e32 v136, v132, v136
	v_mul_f32_e32 v132, v77, v77
	v_fmac_f32_e32 v132, v76, v76
	v_fmac_f32_e32 v132, v78, v78
	v_fmac_f32_e32 v132, v79, v79
	v_add_f32_e32 v136, v132, v136
	v_mul_f32_e32 v137, v105, v105
	v_fmac_f32_e32 v137, v104, v104
	v_fmac_f32_e32 v137, v106, v106
	v_fmac_f32_e32 v137, v107, v107
	v_mul_f32_e32 v132, v101, v101
	v_fmac_f32_e32 v132, v100, v100
	v_fmac_f32_e32 v132, v102, v102
	v_fmac_f32_e32 v132, v103, v103
	v_add_f32_e32 v137, v132, v137
	v_mul_f32_e32 v132, v73, v73
	v_fmac_f32_e32 v132, v72, v72
	v_fmac_f32_e32 v132, v74, v74
	v_fmac_f32_e32 v132, v75, v75
	v_add_f32_e32 v137, v132, v137
	v_mul_f32_e32 v132, v69, v69
	v_fmac_f32_e32 v132, v68, v68
	v_fmac_f32_e32 v132, v70, v70
	v_fmac_f32_e32 v132, v71, v71
	v_add_f32_e32 v137, v132, v137
	v_mul_f32_e32 v138, v65, v65
	v_fmac_f32_e32 v138, v64, v64
	v_fmac_f32_e32 v138, v66, v66
	v_fmac_f32_e32 v138, v67, v67
	v_mul_f32_e32 v132, v61, v61
	v_fmac_f32_e32 v132, v60, v60
	v_fmac_f32_e32 v132, v62, v62
	v_fmac_f32_e32 v132, v63, v63
	v_add_f32_e32 v138, v132, v138
	v_mul_f32_e32 v132, v33, v33
	v_fmac_f32_e32 v132, v32, v32
	v_fmac_f32_e32 v132, v34, v34
	v_fmac_f32_e32 v132, v35, v35
	v_add_f32_e32 v138, v132, v138
	v_mul_f32_e32 v132, v29, v29
	v_fmac_f32_e32 v132, v28, v28
	v_fmac_f32_e32 v132, v30, v30
	v_fmac_f32_e32 v132, v31, v31
	v_add_f32_e32 v138, v132, v138
	v_mul_f32_e32 v139, v57, v57
	v_fmac_f32_e32 v139, v56, v56
	v_fmac_f32_e32 v139, v58, v58
	v_fmac_f32_e32 v139, v59, v59
	v_mul_f32_e32 v132, v53, v53
	v_fmac_f32_e32 v132, v52, v52
	v_fmac_f32_e32 v132, v54, v54
	v_fmac_f32_e32 v132, v55, v55
	v_add_f32_e32 v139, v132, v139
	v_mul_f32_e32 v132, v25, v25
	v_fmac_f32_e32 v132, v24, v24
	v_fmac_f32_e32 v132, v26, v26
	v_fmac_f32_e32 v132, v27, v27
	v_add_f32_e32 v139, v132, v139
	v_mul_f32_e32 v132, v21, v21
	v_fmac_f32_e32 v132, v20, v20
	v_fmac_f32_e32 v132, v22, v22
	v_fmac_f32_e32 v132, v23, v23
	v_add_f32_e32 v139, v132, v139
	v_mul_f32_e32 v140, v49, v49
	v_fmac_f32_e32 v140, v48, v48
	v_fmac_f32_e32 v140, v50, v50
	v_fmac_f32_e32 v140, v51, v51
	v_mul_f32_e32 v132, v45, v45
	v_fmac_f32_e32 v132, v44, v44
	v_fmac_f32_e32 v132, v46, v46
	v_fmac_f32_e32 v132, v47, v47
	v_add_f32_e32 v140, v132, v140
	v_mul_f32_e32 v132, v17, v17
	v_fmac_f32_e32 v132, v16, v16
	v_fmac_f32_e32 v132, v18, v18
	v_fmac_f32_e32 v132, v19, v19
	v_add_f32_e32 v140, v132, v140
	v_mul_f32_e32 v132, v13, v13
	v_fmac_f32_e32 v132, v12, v12
	v_fmac_f32_e32 v132, v14, v14
	v_fmac_f32_e32 v132, v15, v15
	v_add_f32_e32 v140, v132, v140
	v_mul_f32_e32 v141, v41, v41
	v_fmac_f32_e32 v141, v40, v40
	v_fmac_f32_e32 v141, v42, v42
	v_fmac_f32_e32 v141, v43, v43
	v_mul_f32_e32 v132, v37, v37
	v_fmac_f32_e32 v132, v36, v36
	v_fmac_f32_e32 v132, v38, v38
	v_fmac_f32_e32 v132, v39, v39
	v_add_f32_e32 v141, v132, v141
	v_mul_f32_e32 v132, v9, v9
	v_fmac_f32_e32 v132, v8, v8
	v_fmac_f32_e32 v132, v10, v10
	v_fmac_f32_e32 v132, v11, v11
	v_add_f32_e32 v141, v132, v141
	v_mul_f32_e32 v132, v5, v5
	v_fmac_f32_e32 v132, v4, v4
	v_fmac_f32_e32 v132, v6, v6
	v_fmac_f32_e32 v132, v7, v7
	v_add_f32_e32 v141, v132, v141
	ds_bpermute_b32 v142, v215, v134
	ds_bpermute_b32 v143, v215, v135
	ds_bpermute_b32 v144, v215, v136
	ds_bpermute_b32 v145, v215, v137
	ds_bpermute_b32 v146, v215, v138
	ds_bpermute_b32 v147, v215, v139
	ds_bpermute_b32 v148, v215, v140
	ds_bpermute_b32 v149, v215, v141
	s_waitcnt lgkmcnt(0)
	v_add_f32_e32 v134, v134, v142
	v_add_f32_e32 v135, v135, v143
	v_add_f32_e32 v136, v136, v144
	v_add_f32_e32 v137, v137, v145
	v_add_f32_e32 v138, v138, v146
	v_add_f32_e32 v139, v139, v147
	v_add_f32_e32 v140, v140, v148
	v_add_f32_e32 v141, v141, v149
	ds_bpermute_b32 v142, v245, v134
	ds_bpermute_b32 v143, v245, v135
	ds_bpermute_b32 v144, v245, v136
	ds_bpermute_b32 v145, v245, v137
	ds_bpermute_b32 v146, v245, v138
	ds_bpermute_b32 v147, v245, v139
	ds_bpermute_b32 v148, v245, v140
	ds_bpermute_b32 v149, v245, v141
	v_lshl_add_u32 v133, v188, 4, s44
	s_waitcnt lgkmcnt(0)
	s_and_saveexec_b64 s[0:1], s[8:9]
	v_add_f32_e32 v134, v134, v142
	v_add_f32_e32 v135, v135, v143
	v_add_f32_e32 v136, v136, v144
	v_add_f32_e32 v137, v137, v145
	v_add_f32_e32 v138, v138, v146
	v_add_f32_e32 v139, v139, v147
	v_add_f32_e32 v140, v140, v148
	v_add_f32_e32 v141, v141, v149
	ds_write_b32 v133, v134 offset:0
	ds_write_b32 v133, v135 offset:256
	ds_write_b32 v133, v136 offset:512
	ds_write_b32 v133, v137 offset:768
	ds_write_b32 v133, v138 offset:2048
	ds_write_b32 v133, v139 offset:2304
	ds_write_b32 v133, v140 offset:2560
	ds_write_b32 v133, v141 offset:2816
